# diff-attention steady loop: deferred-rescale blocks moved out of line (common path falls through)
# speedup vs baseline: 1.0003x; 1.0003x over previous
; #define WAIT_BAR(N) asm volatile("s_waitcnt vmcnt(" #N ") lgkmcnt(0)\n\ts_barrier" ::: "memory")
; #define RESC() do { if (resc) { asm volatile("s_waitcnt lgkmcnt(0)" ::: "memory"); \
;       _Pragma("unroll") for (int d_ = 0; d_ < 4; ++d_) _Pragma("unroll") for (int r = 0; r < 16; ++r) o[d_][r] *= wsf[crow(r, hi)]; } } while (0)
; #define ROT() do { sl_prev = sl_cur; sl_cur = sl_next; sl_next = (sl_next == 2 * VSLOT) ? 0 : sl_next + VSLOT; } while (0)
; template <int THRL> ...
;     ...
;     int t = 1;
;     for (; t + 4 < NT; t += 2) {
;       STEP(pB0, pB1, pA0, pA1, t, true, true, true, false);                    WAIT_BAR(3);   RESC(); ROT();
.LBB0_419:
	s_add_u32 s34, s30, 0x4000
	s_addc_u32 s35, s31, 0
	s_and_b32 s38, s34, 0x6000
	s_waitcnt lgkmcnt(4)
	v_mfma_f32_32x32x16_bf16 v[2:17], v[122:125], v[130:133], v[2:17]
	ds_read_b64_tr_b16 v[214:215], v225 offset:46080
	ds_read_b64_tr_b16 v[216:217], v225 offset:46592
	v_exp_f32 v98, v98
	v_exp_f32 v99, v99
	v_exp_f32 v127, v100
	s_waitcnt lgkmcnt(4)
	v_mfma_f32_32x32x16_bf16 v[50:65], v[122:125], v[134:137], v[50:65]
	ds_read_b64_tr_b16 v[130:131], v225 offset:34816
	ds_read_b64_tr_b16 v[132:133], v225 offset:35328
	v_exp_f32 v206, v101
	v_exp_f32 v142, v102
	v_exp_f32 v144, v103
	s_waitcnt lgkmcnt(4)
	v_mfma_f32_32x32x16_bf16 v[34:49], v[122:125], v[138:141], v[34:49]
	ds_read_b64_tr_b16 v[100:101], v225 offset:38912
	ds_read_b64_tr_b16 v[102:103], v225 offset:39424
	v_exp_f32 v210, v104
	v_exp_f32 v212, v105
	v_exp_f32 v143, v106
	s_waitcnt lgkmcnt(4)
	v_mfma_f32_32x32x16_bf16 v[18:33], v[122:125], v[214:217], v[18:33]
	ds_read_b64_tr_b16 v[134:135], v225 offset:43008
	ds_read_b64_tr_b16 v[136:137], v225 offset:43520
	v_exp_f32 v122, v107
	v_exp_f32 v123, v108
	v_exp_f32 v209, v109
	s_waitcnt lgkmcnt(4)
	v_mfma_f32_32x32x16_bf16 v[2:17], v[118:121], v[130:133], v[2:17]
	ds_read_b64_tr_b16 v[104:105], v225 offset:47104
	ds_read_b64_tr_b16 v[106:107], v225 offset:47616
	v_exp_f32 v208, v110
	v_exp_f32 v211, v111
	v_exp_f32 v203, v112
	s_waitcnt lgkmcnt(4)
	v_mfma_f32_32x32x16_bf16 v[50:65], v[118:121], v[100:103], v[50:65]
	ds_read_b64_tr_b16 v[108:109], v225 offset:35840
	ds_read_b64_tr_b16 v[110:111], v225 offset:36352
	v_exp_f32 v220, v113
	v_exp_f32 v204, v82
	v_exp_f32 v207, v83
	s_waitcnt lgkmcnt(4)
	v_mfma_f32_32x32x16_bf16 v[34:49], v[118:121], v[134:137], v[34:49]
	ds_read_b64_tr_b16 v[100:101], v225 offset:39936
	ds_read_b64_tr_b16 v[102:103], v225 offset:40448
	v_exp_f32 v216, v84
	v_exp_f32 v218, v85
	v_exp_f32 v145, v86
	s_waitcnt lgkmcnt(4)
	v_mfma_f32_32x32x16_bf16 v[18:33], v[118:121], v[104:107], v[18:33]
	ds_read_b64_tr_b16 v[138:139], v225 offset:44032
	ds_read_b64_tr_b16 v[140:141], v225 offset:44544
	v_exp_f32 v219, v87
	v_exp_f32 v213, v88
	v_exp_f32 v214, v89
	s_waitcnt lgkmcnt(4)
	v_mfma_f32_32x32x16_bf16 v[2:17], v[114:117], v[108:111], v[2:17]
	v_add_u32_e32 v118, s38, v191
	ds_read_b64_tr_b16 v[86:87], v225 offset:48128
	ds_read_b64_tr_b16 v[88:89], v225 offset:48640
	ds_read_b128 v[82:85], v118
	v_exp_f32 v215, v90
	v_exp_f32 v217, v91
	s_waitcnt lgkmcnt(5)
	v_mfma_f32_32x32x16_bf16 v[50:65], v[114:117], v[100:103], v[50:65]
	ds_read_b128 v[130:133], v118 offset:512
	v_exp_f32 v221, v92
	v_exp_f32 v223, v93
	s_waitcnt lgkmcnt(4)
	v_mfma_f32_32x32x16_bf16 v[34:49], v[114:117], v[138:141], v[34:49]
	ds_read_b128 v[134:137], v118 offset:2048
	v_exp_f32 v222, v94
	v_exp_f32 v224, v95
	s_waitcnt lgkmcnt(3)
	v_mfma_f32_32x32x16_bf16 v[18:33], v[114:117], v[86:89], v[18:33]
	v_exp_f32 v225, v96
	v_exp_f32 v226, v97
	s_waitcnt vmcnt(3) lgkmcnt(0)
	s_barrier
	s_and_b64 vcc, exec, s[36:37]
	s_cbranch_vccnz .Lda_resc_odd

; #define SJ_DRAIN() do { if (sjp) { att::side_drain(SJ, sj, tid, shm); ++sj; sjp = false; } } while (0)
; #define SJ_WAIT_BAR() do { if (sji) { WAIT_BAR(5); sji = false; } else { WAIT_BAR(3); } } while (0)
; #define RESC() do { if (resc) { asm volatile("s_waitcnt lgkmcnt(0)" ::: "memory"); \
;       _Pragma("unroll") for (int d_ = 0; d_ < 4; ++d_) _Pragma("unroll") for (int r = 0; r < 16; ++r) o[d_][r] *= wsf[crow(r, hi)]; } } while (0)
; #define ROT() do { sl_prev = sl_cur; sl_cur = sl_next; sl_next = (sl_next == 2 * VSLOT) ? 0 : sl_next + VSLOT; } while (0)
; template <int THRL> ...
;     ...
;       SJ_DRAIN(); STEP(pA0, pA1, pB0, pB1, t + 1, true, true, true, true);     SJ_WAIT_BAR(); RESC(); ROT();
.LBB0_445:
	s_and_b64 vcc, exec, s[38:39]
	s_cbranch_vccnz .LBB0_446

.Lda_resc_odd:
	s_waitcnt lgkmcnt(0)
	v_add_u32_e32 v100, s80, v152
	ds_read_b128 v[86:89], v100 offset:96
	ds_read_b128 v[90:93], v100 offset:64
	ds_read_b128 v[94:97], v100 offset:32
	ds_read_b128 v[100:103], v100
	s_waitcnt lgkmcnt(3)
	v_pk_mul_f32 v[14:15], v[14:15], v[86:87]
	s_waitcnt lgkmcnt(2)
	v_pk_mul_f32 v[10:11], v[10:11], v[90:91]
	s_waitcnt lgkmcnt(1)
	v_pk_mul_f32 v[6:7], v[6:7], v[94:95]
	v_pk_mul_f32 v[16:17], v[16:17], v[88:89]
	v_pk_mul_f32 v[12:13], v[12:13], v[92:93]
	v_pk_mul_f32 v[8:9], v[8:9], v[96:97]
	s_waitcnt lgkmcnt(0)
	v_pk_mul_f32 v[4:5], v[4:5], v[102:103]
	v_pk_mul_f32 v[2:3], v[2:3], v[100:101]
	v_pk_mul_f32 v[62:63], v[62:63], v[86:87]
	v_pk_mul_f32 v[58:59], v[58:59], v[90:91]
	v_pk_mul_f32 v[54:55], v[54:55], v[94:95]
	v_pk_mul_f32 v[64:65], v[64:65], v[88:89]
	v_pk_mul_f32 v[60:61], v[60:61], v[92:93]
	v_pk_mul_f32 v[56:57], v[56:57], v[96:97]
	v_pk_mul_f32 v[52:53], v[52:53], v[102:103]
	v_pk_mul_f32 v[50:51], v[50:51], v[100:101]
	v_pk_mul_f32 v[46:47], v[46:47], v[86:87]
	v_pk_mul_f32 v[42:43], v[42:43], v[90:91]
	v_pk_mul_f32 v[38:39], v[38:39], v[94:95]
	v_pk_mul_f32 v[48:49], v[48:49], v[88:89]
	v_pk_mul_f32 v[44:45], v[44:45], v[92:93]
	v_pk_mul_f32 v[40:41], v[40:41], v[96:97]
	v_pk_mul_f32 v[36:37], v[36:37], v[102:103]
	v_pk_mul_f32 v[34:35], v[34:35], v[100:101]
	v_pk_mul_f32 v[30:31], v[30:31], v[86:87]
	v_pk_mul_f32 v[26:27], v[26:27], v[90:91]
	v_pk_mul_f32 v[22:23], v[22:23], v[94:95]
	v_pk_mul_f32 v[32:33], v[32:33], v[88:89]
	v_pk_mul_f32 v[28:29], v[28:29], v[92:93]
	v_pk_mul_f32 v[24:25], v[24:25], v[96:97]
	v_pk_mul_f32 v[20:21], v[20:21], v[102:103]
	v_pk_mul_f32 v[18:19], v[18:19], v[100:101]
	s_branch .LBB0_421
